# per-XCD start stagger (blockIdx%8 x 3us) at the four residual-epilogue GEMM phases, on top of v8
# baseline (speedup 1.0000x reference)
; #define PG8_LAS __attribute__((address_space(3)))
;     __device__ __forceinline__ bool next(int i, Unit& u) const { const int k = r + i * R; if (k >= n) return false; u.pm = k / nN; u.pn = k % nN; return true; }
;     __host__ __device__ bool next(int i, Unit& u) const {
;         const long L = (long)i * G + c; if (L >= nwg) return false;
;         int wgid = (int)L; { const int q = nwg / NXCD, r = nwg % NXCD, xcd = wgid % NXCD, off = wgid / NXCD; wgid = (xcd < r ? xcd * (q + 1) : r * (q + 1) + (xcd - r) * q) + off; }
;         const int nig = WGM * nN, gid = wgid / nig, fm = gid * WGM, gsz = (nM - fm) < WGM ? (nM - fm) : WGM;
;         u.pm = fm + ((wgid % nig) % gsz); u.pn = (wgid % nig) / gsz; return true;
; template <class Epi, class Sched, bool ALIGN_EPI = false, bool SP2 = false>
; __device__ __forceinline__ void gemm_phase(PG8_LAS unsigned char* lds, const Gemm g, const Sched& S, const Epi& E) {
;     int tid_ = threadIdx.x; asm volatile("" : "+v"(tid_));
;     const int tid = tid_, wid = __builtin_amdgcn_readfirstlane(tid >> 6), lane = tid & 63, wr = wid >> 2, wc = wid & 3, fr = lane & 15, fq = lane >> 4;
.LBB0_676:
	s_or_b64 exec, exec, s[42:43]
	s_mov_b64 s[8:9], s[0:1]
	v_mov_b32_e32 v8, v220
	s_waitcnt lgkmcnt(0)
	s_barrier
	s_and_b32 s98, s2, 7
	s_mul_i32 s98, s98, 300
	s_memrealtime s[100:101]
	s_waitcnt lgkmcnt(0)
	s_add_u32 s99, s100, s98
.Lstg_p6:
	s_memrealtime s[100:101]
	s_waitcnt lgkmcnt(0)
	s_sub_u32 s100, s100, s99
	s_cmp_lt_i32 s100, 0
	s_cbranch_scc0 .Lstg_done_p6
	s_sleep 2
	s_branch .Lstg_p6
.Lstg_done_p6:
	s_and_b64 vcc, exec, s[4:5]
	v_readfirstlane_b32 s26, v8
	s_cbranch_vccnz .LBB0_682
	s_ashr_i32 s10, s2, 31
	s_lshr_b32 s10, s10, 29
	s_add_i32 s12, s2, s10
	s_and_b32 s10, s12, -8
	s_sub_i32 s13, s2, s10
	s_cmp_gt_i32 s13, -1
	s_cbranch_scc0 .LBB0_679
	s_lshl_b32 s14, s13, 6
	s_cbranch_execz .LBB0_680
	s_branch .LBB0_681

; __device__ __forceinline__ void xcd_barrier(const XcdBarrier& b) {
;     ...
;     __syncthreads();
.LBB0_1117:
	s_or_b64 exec, exec, s[50:51]
	s_mov_b64 s[10:11], s[0:1]
	v_mov_b32_e32 v8, v220
	s_waitcnt lgkmcnt(0)
	s_barrier
	s_and_b32 s98, s2, 7
	s_mul_i32 s98, s98, 300
	s_memrealtime s[100:101]
	s_waitcnt lgkmcnt(0)
	s_add_u32 s99, s100, s98

;     __device__ __forceinline__ bool next(int i, Unit& u) const { const int k = r + i * R; if (k >= n) return false; u.pm = k / nN; u.pn = k % nN; return true; }
;     __host__ __device__ bool next(int i, Unit& u) const {
;         const long L = (long)i * G + c; if (L >= nwg) return false;
;         int wgid = (int)L; { const int q = nwg / NXCD, r = nwg % NXCD, xcd = wgid % NXCD, off = wgid / NXCD; wgid = (xcd < r ? xcd * (q + 1) : r * (q + 1) + (xcd - r) * q) + off; }
;         const int nig = WGM * nN, gid = wgid / nig, fm = gid * WGM, gsz = (nM - fm) < WGM ? (nM - fm) : WGM;
;         u.pm = fm + ((wgid % nig) % gsz); u.pn = (wgid % nig) / gsz; return true;
; template <class Epi, class Sched, bool ALIGN_EPI = false, bool SP2 = false>
; __device__ __forceinline__ void gemm_phase(PG8_LAS unsigned char* lds, const Gemm g, const Sched& S, const Epi& E) {
;     ...
;     const int tid = tid_, wid = __builtin_amdgcn_readfirstlane(tid >> 6), lane = tid & 63, wr = wid >> 2, wc = wid & 3, fr = lane & 15, fq = lane >> 4;
.Lstg_done_p10:
	s_and_b64 vcc, exec, s[4:5]
	v_readfirstlane_b32 s14, v8
	s_cbranch_vccnz .LBB0_1123
	s_ashr_i32 s12, s2, 31
	s_lshr_b32 s12, s12, 29
	s_add_i32 s15, s2, s12
	s_and_b32 s12, s15, -8
	s_sub_i32 s18, s2, s12
	s_cmp_gt_i32 s18, -1
	s_cbranch_scc0 .LBB0_1120
	s_lshl_b32 s19, s18, 6
	s_cbranch_execz .LBB0_1121
	s_branch .LBB0_1122

; __device__ __forceinline__ void xcd_barrier(const XcdBarrier& b) {
;     ...
;     __syncthreads();
.LBB0_1457:
	s_or_b64 exec, exec, s[42:43]
	s_mov_b64 s[6:7], s[0:1]
	v_mov_b32_e32 v8, v220
	s_waitcnt lgkmcnt(0)
	s_barrier
	s_and_b32 s98, s2, 7
	s_mul_i32 s98, s98, 300
	s_memrealtime s[100:101]
	s_waitcnt lgkmcnt(0)
	s_add_u32 s99, s100, s98

;     __device__ __forceinline__ bool next(int i, Unit& u) const { const int k = r + i * R; if (k >= n) return false; u.pm = k / nN; u.pn = k % nN; return true; }
;     __host__ __device__ bool next(int i, Unit& u) const {
;         const long L = (long)i * G + c; if (L >= nwg) return false;
;         int wgid = (int)L; { const int q = nwg / NXCD, r = nwg % NXCD, xcd = wgid % NXCD, off = wgid / NXCD; wgid = (xcd < r ? xcd * (q + 1) : r * (q + 1) + (xcd - r) * q) + off; }
;         const int nig = WGM * nN, gid = wgid / nig, fm = gid * WGM, gsz = (nM - fm) < WGM ? (nM - fm) : WGM;
;         u.pm = fm + ((wgid % nig) % gsz); u.pn = (wgid % nig) / gsz; return true;
; template <class Epi, class Sched, bool ALIGN_EPI = false, bool SP2 = false>
; __device__ __forceinline__ void gemm_phase(PG8_LAS unsigned char* lds, const Gemm g, const Sched& S, const Epi& E) {
;     ...
;     const int tid = tid_, wid = __builtin_amdgcn_readfirstlane(tid >> 6), lane = tid & 63, wr = wid >> 2, wc = wid & 3, fr = lane & 15, fq = lane >> 4;
.Lstg_done_p14:
	s_and_b64 vcc, exec, s[4:5]
	v_readfirstlane_b32 s24, v8
	s_cbranch_vccnz .LBB0_1463
	s_ashr_i32 s10, s2, 31
	s_lshr_b32 s10, s10, 29
	s_add_i32 s12, s2, s10
	s_and_b32 s10, s12, -8
	s_sub_i32 s13, s2, s10
	s_cmp_gt_i32 s13, -1
	s_cbranch_scc0 .LBB0_1460
	s_lshl_b32 s14, s13, 6
	s_cbranch_execz .LBB0_1461
	s_branch .LBB0_1462

; __device__ __forceinline__ void xcd_barrier(const XcdBarrier& b) {
;     ...
;     __syncthreads();
.LBB0_1878:
	s_or_b64 exec, exec, s[38:39]
	s_waitcnt lgkmcnt(0)
	s_barrier
	s_and_b32 s98, s2, 7
	s_mul_i32 s98, s98, 300
	s_memrealtime s[100:101]
	s_waitcnt lgkmcnt(0)
	s_add_u32 s99, s100, s98

;     __device__ __forceinline__ bool next(int i, Unit& u) const { const int k = r + i * R; if (k >= n) return false; u.pm = k / nN; u.pn = k % nN; return true; }
;     __host__ __device__ bool next(int i, Unit& u) const {
;         const long L = (long)i * G + c; if (L >= nwg) return false;
;         int wgid = (int)L; { const int q = nwg / NXCD, r = nwg % NXCD, xcd = wgid % NXCD, off = wgid / NXCD; wgid = (xcd < r ? xcd * (q + 1) : r * (q + 1) + (xcd - r) * q) + off; }
;         const int nig = WGM * nN, gid = wgid / nig, fm = gid * WGM, gsz = (nM - fm) < WGM ? (nM - fm) : WGM;
;         u.pm = fm + ((wgid % nig) % gsz); u.pn = (wgid % nig) / gsz; return true;
; template <class Epi, class Sched, bool ALIGN_EPI = false, bool SP2 = false>
; __device__ __forceinline__ void gemm_phase(PG8_LAS unsigned char* lds, const Gemm g, const Sched& S, const Epi& E) {
;     ...
;     const int tid = tid_, wid = __builtin_amdgcn_readfirstlane(tid >> 6), lane = tid & 63, wr = wid >> 2, wc = wid & 3, fr = lane & 15, fq = lane >> 4;
.Lstg_done_p18:
	s_and_b64 vcc, exec, s[4:5]
	v_readfirstlane_b32 s14, v220
	s_cbranch_vccnz .LBB0_1906
	s_ashr_i32 s3, s2, 31
	s_lshr_b32 s4, s3, 29
	s_add_i32 s12, s2, s4
	s_and_b32 s4, s12, -8
	s_sub_i32 s7, s2, s4
	s_cmp_gt_i32 s7, -1
	s_cbranch_scc0 .LBB0_1881
	s_lshl_b32 s6, s7, 6
	s_load_dwordx4 s[8:11], s[0:1], 0xe8
	s_ashr_i32 s4, s12, 3
	s_cbranch_execz .LBB0_1882
	s_branch .LBB0_1883
